# P4 and P6 epilogues: row-sum xor-16/32 shuffles via v_permlane16/32_swap instead of ds_bpermute round trips
# speedup vs baseline: 1.0082x; 1.0016x over previous
.LBB0_978:
	s_or_b64 exec, exec, s[26:27]
	v_mul_f32_e32 v133, v9, v9
	v_mul_f32_e32 v160, v11, v11
	v_fmac_f32_e32 v133, v8, v8
	v_fmac_f32_e32 v160, v10, v10
	v_add_f32_e32 v133, v133, v160
	v_mul_f32_e32 v160, v5, v5
	v_fmac_f32_e32 v160, v4, v4
	v_add_f32_e32 v133, v133, v160
	v_mul_f32_e32 v160, v7, v7
	v_fmac_f32_e32 v160, v6, v6
	v_add_f32_e32 v133, v160, v133
	v_mul_f32_e32 v160, v33, v33
	v_mul_f32_e32 v161, v35, v35
	v_fmac_f32_e32 v160, v32, v32
	v_fmac_f32_e32 v161, v34, v34
	v_add_f32_e32 v160, v160, v161
	v_mul_f32_e32 v161, v29, v29
	v_fmac_f32_e32 v161, v28, v28
	v_add_f32_e32 v160, v160, v161
	v_mul_f32_e32 v161, v31, v31
	v_fmac_f32_e32 v161, v30, v30
	v_add_f32_e32 v160, v161, v160
	v_and_b32_e32 v161, 64, v168
	v_add_f32_e32 v160, v133, v160
	v_xor_b32_e32 v133, 16, v168
	v_add_u32_e32 v161, 64, v161
	v_cmp_lt_i32_e32 vcc, v133, v161
	s_lshl_b32 s26, s16, 2
	s_ashr_i32 s27, s26, 31
	v_cndmask_b32_e32 v133, v168, v133, vcc
	v_lshlrev_b32_e32 v133, 2, v133
	v_mov_b32_e32 v169, v160
	s_nop 1
	v_permlane16_swap_b32 v160, v169
	global_store_dwordx4 v[154:155], v[134:137], off
	global_store_dwordx4 v[152:153], v[138:141], off
	s_waitcnt lgkmcnt(0)
	v_add_f32_e32 v160, v160, v169
	v_xor_b32_e32 v169, 32, v168
	v_cmp_lt_i32_e32 vcc, v169, v161
	s_nop 1
	v_cndmask_b32_e32 v161, v168, v169, vcc
	v_lshlrev_b32_e32 v169, 2, v161
	v_mov_b32_e32 v161, v160
	s_nop 1
	v_permlane32_swap_b32 v160, v161
	s_and_saveexec_b64 s[70:71], s[10:11]
	s_cbranch_execz .LBB0_980
	v_lshlrev_b64 v[134:135], 6, v[150:151]
	v_lshl_add_u64 v[134:135], s[0:1], 0, v[134:135]
	v_lshl_add_u64 v[134:135], s[26:27], 2, v[134:135]
	s_lshl_b32 s54, s3, 2
	v_lshl_add_u64 v[134:135], v[134:135], 0, s[54:55]
	s_waitcnt lgkmcnt(0)
	v_add_f32_e32 v136, v160, v161
	global_store_dword v[134:135], v136, off

.LBB0_982:
	s_or_b64 exec, exec, s[70:71]
	v_mul_f32_e32 v151, v13, v13
	v_mul_f32_e32 v170, v15, v15
	v_fmac_f32_e32 v151, v12, v12
	v_fmac_f32_e32 v170, v14, v14
	v_add_f32_e32 v151, v151, v170
	v_mul_f32_e32 v170, v17, v17
	v_fmac_f32_e32 v170, v16, v16
	v_add_f32_e32 v151, v151, v170
	v_mul_f32_e32 v170, v19, v19
	v_fmac_f32_e32 v170, v18, v18
	v_add_f32_e32 v151, v170, v151
	v_mul_f32_e32 v170, v41, v41
	v_mul_f32_e32 v171, v43, v43
	v_fmac_f32_e32 v170, v40, v40
	v_fmac_f32_e32 v171, v42, v42
	v_add_f32_e32 v170, v170, v171
	v_mul_f32_e32 v171, v53, v53
	v_fmac_f32_e32 v171, v52, v52
	v_add_f32_e32 v170, v170, v171
	v_mul_f32_e32 v171, v55, v55
	v_fmac_f32_e32 v171, v54, v54
	v_add_f32_e32 v170, v171, v170
	v_add_f32_e32 v151, v151, v170
	v_mov_b32_e32 v170, v151
	s_nop 1
	v_permlane16_swap_b32 v151, v170
	global_store_dwordx4 v[160:161], v[134:137], off
	global_store_dwordx4 v[154:155], v[138:141], off
	s_waitcnt lgkmcnt(0)
	v_add_f32_e32 v151, v151, v170
	v_mov_b32_e32 v170, v151
	s_nop 1
	v_permlane32_swap_b32 v151, v170
	s_and_saveexec_b64 s[70:71], s[10:11]
	s_cbranch_execz .LBB0_984
	v_lshlrev_b64 v[134:135], 6, v[152:153]
	v_lshl_add_u64 v[134:135], s[0:1], 0, v[134:135]
	v_lshl_add_u64 v[134:135], s[26:27], 2, v[134:135]
	s_lshl_b32 s54, s3, 2
	v_lshl_add_u64 v[134:135], v[134:135], 0, s[54:55]
	s_waitcnt lgkmcnt(0)
	v_add_f32_e32 v136, v151, v170
	global_store_dword v[134:135], v136, off

.LBB0_986:
	s_or_b64 exec, exec, s[70:71]
	v_mul_f32_e32 v151, v45, v45
	v_mul_f32_e32 v170, v47, v47
	v_fmac_f32_e32 v151, v44, v44
	v_fmac_f32_e32 v170, v46, v46
	v_add_f32_e32 v151, v151, v170
	v_mul_f32_e32 v170, v37, v37
	v_fmac_f32_e32 v170, v36, v36
	v_add_f32_e32 v151, v151, v170
	v_mul_f32_e32 v170, v39, v39
	v_fmac_f32_e32 v170, v38, v38
	v_add_f32_e32 v151, v170, v151
	v_mul_f32_e32 v170, v49, v49
	v_mul_f32_e32 v171, v51, v51
	v_fmac_f32_e32 v170, v48, v48
	v_fmac_f32_e32 v171, v50, v50
	v_add_f32_e32 v170, v170, v171
	v_mul_f32_e32 v171, v61, v61
	v_fmac_f32_e32 v171, v60, v60
	v_add_f32_e32 v170, v170, v171
	v_mul_f32_e32 v171, v63, v63
	v_fmac_f32_e32 v171, v62, v62
	v_add_f32_e32 v170, v171, v170
	v_add_f32_e32 v151, v151, v170
	v_mov_b32_e32 v170, v151
	s_nop 1
	v_permlane16_swap_b32 v151, v170
	global_store_dwordx4 v[160:161], v[134:137], off
	global_store_dwordx4 v[154:155], v[138:141], off
	s_waitcnt lgkmcnt(0)
	v_add_f32_e32 v151, v151, v170
	v_mov_b32_e32 v170, v151
	s_nop 1
	v_permlane32_swap_b32 v151, v170
	s_and_saveexec_b64 s[70:71], s[10:11]
	s_cbranch_execz .LBB0_988
	v_lshlrev_b64 v[134:135], 6, v[152:153]
	v_lshl_add_u64 v[134:135], s[0:1], 0, v[134:135]
	v_lshl_add_u64 v[134:135], s[26:27], 2, v[134:135]
	s_lshl_b32 s54, s3, 2
	v_lshl_add_u64 v[134:135], v[134:135], 0, s[54:55]
	s_waitcnt lgkmcnt(0)
	v_add_f32_e32 v136, v151, v170
	global_store_dword v[134:135], v136, off

.LBB0_990:
	s_or_b64 exec, exec, s[70:71]
	v_mul_f32_e32 v151, v21, v21
	v_mul_f32_e32 v170, v23, v23
	v_fmac_f32_e32 v151, v20, v20
	v_fmac_f32_e32 v170, v22, v22
	v_add_f32_e32 v151, v151, v170
	v_mul_f32_e32 v170, v25, v25
	v_fmac_f32_e32 v170, v24, v24
	v_add_f32_e32 v151, v151, v170
	v_mul_f32_e32 v170, v27, v27
	v_fmac_f32_e32 v170, v26, v26
	v_add_f32_e32 v151, v170, v151
	v_mul_f32_e32 v170, v57, v57
	v_mul_f32_e32 v171, v59, v59
	v_fmac_f32_e32 v170, v56, v56
	v_fmac_f32_e32 v171, v58, v58
	v_add_f32_e32 v170, v170, v171
	v_mul_f32_e32 v171, v65, v65
	v_fmac_f32_e32 v171, v64, v64
	v_add_f32_e32 v170, v170, v171
	v_mul_f32_e32 v171, v67, v67
	v_fmac_f32_e32 v171, v66, v66
	v_add_f32_e32 v170, v171, v170
	v_add_f32_e32 v151, v151, v170
	v_mov_b32_e32 v170, v151
	s_nop 1
	v_permlane16_swap_b32 v151, v170
	global_store_dwordx4 v[160:161], v[134:137], off
	global_store_dwordx4 v[154:155], v[138:141], off
	s_waitcnt lgkmcnt(0)
	v_add_f32_e32 v151, v151, v170
	v_mov_b32_e32 v170, v151
	s_nop 1
	v_permlane32_swap_b32 v151, v170
	s_and_saveexec_b64 s[70:71], s[10:11]
	s_cbranch_execz .LBB0_992
	v_lshlrev_b64 v[134:135], 6, v[152:153]
	v_lshl_add_u64 v[134:135], s[0:1], 0, v[134:135]
	v_lshl_add_u64 v[134:135], s[26:27], 2, v[134:135]
	s_lshl_b32 s54, s3, 2
	v_lshl_add_u64 v[134:135], v[134:135], 0, s[54:55]
	s_waitcnt lgkmcnt(0)
	v_add_f32_e32 v136, v151, v170
	global_store_dword v[134:135], v136, off

.LBB0_994:
	s_or_b64 exec, exec, s[70:71]
	v_mul_f32_e32 v151, v69, v69
	v_mul_f32_e32 v170, v71, v71
	v_fmac_f32_e32 v151, v68, v68
	v_fmac_f32_e32 v170, v70, v70
	v_add_f32_e32 v151, v151, v170
	v_mul_f32_e32 v170, v73, v73
	v_fmac_f32_e32 v170, v72, v72
	v_add_f32_e32 v151, v151, v170
	v_mul_f32_e32 v170, v75, v75
	v_fmac_f32_e32 v170, v74, v74
	v_add_f32_e32 v151, v170, v151
	v_mul_f32_e32 v170, v89, v89
	v_mul_f32_e32 v171, v91, v91
	v_fmac_f32_e32 v170, v88, v88
	v_fmac_f32_e32 v171, v90, v90
	v_add_f32_e32 v170, v170, v171
	v_mul_f32_e32 v171, v101, v101
	v_fmac_f32_e32 v171, v100, v100
	v_add_f32_e32 v170, v170, v171
	v_mul_f32_e32 v171, v103, v103
	v_fmac_f32_e32 v171, v102, v102
	v_add_f32_e32 v170, v171, v170
	v_add_f32_e32 v151, v151, v170
	v_mov_b32_e32 v170, v151
	s_nop 1
	v_permlane16_swap_b32 v151, v170
	global_store_dwordx4 v[160:161], v[134:137], off
	global_store_dwordx4 v[154:155], v[138:141], off
	s_waitcnt lgkmcnt(0)
	v_add_f32_e32 v151, v151, v170
	v_mov_b32_e32 v170, v151
	s_nop 1
	v_permlane32_swap_b32 v151, v170
	s_and_saveexec_b64 s[70:71], s[10:11]
	s_cbranch_execz .LBB0_996
	v_lshlrev_b64 v[134:135], 6, v[152:153]
	v_lshl_add_u64 v[134:135], s[0:1], 0, v[134:135]
	v_lshl_add_u64 v[134:135], s[26:27], 2, v[134:135]
	s_lshl_b32 s54, s3, 2
	v_lshl_add_u64 v[134:135], v[134:135], 0, s[54:55]
	s_waitcnt lgkmcnt(0)
	v_add_f32_e32 v136, v151, v170
	global_store_dword v[134:135], v136, off

.LBB0_998:
	s_or_b64 exec, exec, s[70:71]
	v_mul_f32_e32 v151, v93, v93
	v_mul_f32_e32 v170, v95, v95
	v_fmac_f32_e32 v151, v92, v92
	v_fmac_f32_e32 v170, v94, v94
	v_add_f32_e32 v151, v151, v170
	v_mul_f32_e32 v170, v85, v85
	v_fmac_f32_e32 v170, v84, v84
	v_add_f32_e32 v151, v151, v170
	v_mul_f32_e32 v170, v87, v87
	v_fmac_f32_e32 v170, v86, v86
	v_add_f32_e32 v151, v170, v151
	v_mul_f32_e32 v170, v97, v97
	v_mul_f32_e32 v171, v99, v99
	v_fmac_f32_e32 v170, v96, v96
	v_fmac_f32_e32 v171, v98, v98
	v_add_f32_e32 v170, v170, v171
	v_mul_f32_e32 v171, v105, v105
	v_fmac_f32_e32 v171, v104, v104
	v_add_f32_e32 v170, v170, v171
	v_mul_f32_e32 v171, v107, v107
	v_fmac_f32_e32 v171, v106, v106
	v_add_f32_e32 v170, v171, v170
	v_add_f32_e32 v151, v151, v170
	v_mov_b32_e32 v170, v151
	s_nop 1
	v_permlane16_swap_b32 v151, v170
	global_store_dwordx4 v[160:161], v[134:137], off
	global_store_dwordx4 v[154:155], v[138:141], off
	s_waitcnt lgkmcnt(0)
	v_add_f32_e32 v151, v151, v170
	v_mov_b32_e32 v170, v151
	s_nop 1
	v_permlane32_swap_b32 v151, v170
	s_and_saveexec_b64 s[70:71], s[10:11]
	s_cbranch_execz .LBB0_1000
	v_lshlrev_b64 v[134:135], 6, v[152:153]
	v_lshl_add_u64 v[134:135], s[0:1], 0, v[134:135]
	v_lshl_add_u64 v[134:135], s[26:27], 2, v[134:135]
	s_lshl_b32 s54, s3, 2
	v_lshl_add_u64 v[134:135], v[134:135], 0, s[54:55]
	s_waitcnt lgkmcnt(0)
	v_add_f32_e32 v136, v151, v170
	global_store_dword v[134:135], v136, off

.LBB0_1002:
	s_or_b64 exec, exec, s[70:71]
	v_mul_f32_e32 v151, v77, v77
	v_mul_f32_e32 v170, v79, v79
	v_fmac_f32_e32 v151, v76, v76
	v_fmac_f32_e32 v170, v78, v78
	v_add_f32_e32 v151, v151, v170
	v_mul_f32_e32 v170, v81, v81
	v_fmac_f32_e32 v170, v80, v80
	v_add_f32_e32 v151, v151, v170
	v_mul_f32_e32 v170, v83, v83
	v_fmac_f32_e32 v170, v82, v82
	v_add_f32_e32 v151, v170, v151
	v_mul_f32_e32 v170, v113, v113
	v_mul_f32_e32 v171, v115, v115
	v_fmac_f32_e32 v170, v112, v112
	v_fmac_f32_e32 v171, v114, v114
	v_add_f32_e32 v170, v170, v171
	v_mul_f32_e32 v171, v125, v125
	v_fmac_f32_e32 v171, v124, v124
	v_add_f32_e32 v170, v170, v171
	v_mul_f32_e32 v171, v127, v127
	v_fmac_f32_e32 v171, v126, v126
	v_add_f32_e32 v170, v171, v170
	v_add_f32_e32 v151, v151, v170
	v_mov_b32_e32 v170, v151
	s_nop 1
	v_permlane16_swap_b32 v151, v170
	global_store_dwordx4 v[160:161], v[134:137], off
	global_store_dwordx4 v[154:155], v[138:141], off
	s_waitcnt lgkmcnt(0)
	v_add_f32_e32 v151, v151, v170
	v_mov_b32_e32 v170, v151
	s_nop 1
	v_permlane32_swap_b32 v151, v170
	s_and_saveexec_b64 s[70:71], s[10:11]
	s_cbranch_execz .LBB0_1004
	v_lshlrev_b64 v[134:135], 6, v[152:153]
	v_lshl_add_u64 v[134:135], s[0:1], 0, v[134:135]
	v_lshl_add_u64 v[134:135], s[26:27], 2, v[134:135]
	s_lshl_b32 s54, s3, 2
	v_lshl_add_u64 v[134:135], v[134:135], 0, s[54:55]
	s_waitcnt lgkmcnt(0)
	v_add_f32_e32 v136, v151, v170
	global_store_dword v[134:135], v136, off

.LBB0_1006:
	s_or_b64 exec, exec, s[70:71]
	v_mul_f32_e32 v154, v117, v117
	v_mul_f32_e32 v155, v119, v119
	v_fmac_f32_e32 v154, v116, v116
	v_fmac_f32_e32 v155, v118, v118
	v_add_f32_e32 v154, v154, v155
	v_mul_f32_e32 v155, v109, v109
	v_fmac_f32_e32 v155, v108, v108
	v_add_f32_e32 v154, v154, v155
	v_mul_f32_e32 v155, v111, v111
	v_fmac_f32_e32 v155, v110, v110
	v_add_f32_e32 v154, v155, v154
	v_mul_f32_e32 v155, v121, v121
	v_mul_f32_e32 v160, v123, v123
	v_fmac_f32_e32 v155, v120, v120
	v_fmac_f32_e32 v160, v122, v122
	v_add_f32_e32 v155, v155, v160
	v_mul_f32_e32 v160, v129, v129
	v_fmac_f32_e32 v160, v128, v128
	v_add_f32_e32 v155, v155, v160
	v_mul_f32_e32 v160, v131, v131
	v_fmac_f32_e32 v160, v130, v130
	v_add_f32_e32 v155, v160, v155
	v_add_f32_e32 v154, v154, v155
	v_mov_b32_e32 v133, v154
	s_nop 1
	v_permlane16_swap_b32 v154, v133
	global_store_dwordx4 v[152:153], v[134:137], off
	global_store_dwordx4 v[148:149], v[138:141], off
	s_waitcnt lgkmcnt(0)
	v_add_f32_e32 v133, v154, v133
	v_mov_b32_e32 v154, v133
	s_nop 1
	v_permlane32_swap_b32 v133, v154
	s_and_saveexec_b64 s[70:71], s[10:11]
	s_cbranch_execz .LBB0_1008
	v_lshlrev_b64 v[134:135], 6, v[150:151]
	v_lshl_add_u64 v[134:135], s[0:1], 0, v[134:135]
	v_lshl_add_u64 v[134:135], s[26:27], 2, v[134:135]
	s_lshl_b32 s54, s3, 2
	v_lshl_add_u64 v[134:135], v[134:135], 0, s[54:55]
	s_waitcnt lgkmcnt(0)
	v_add_f32_e32 v133, v133, v154
	global_store_dword v[134:135], v133, off

.LBB0_1376:
	s_lshl_b32 s18, s8, 8
	s_add_i32 s2, s18, s62
	v_or_b32_e32 v166, s2, v3
	s_lshl_b32 s2, s0, 8
	s_lshl_b32 s3, s9, 6
	s_or_b32 s2, s2, s3
	v_ashrrev_i32_e32 v167, 31, v166
	v_lshl_or_b32 v0, v142, 3, s2
	v_cmp_gt_u32_e64 s[2:3], 8, v3
	v_mov_b32_e32 v3, 0xffffc040
	v_lshlrev_b64 v[132:133], 11, v[166:167]
	v_ashrrev_i32_e32 v1, 31, v0
	v_cndmask_b32_e64 v162, v3, 0, s[2:3]
	v_mov_b32_e32 v3, 0x4040
	v_lshl_add_u64 v[132:133], s[42:43], 0, v[132:133]
	v_cndmask_b32_e64 v163, -1, 0, s[2:3]
	v_cndmask_b32_e64 v164, 0, v3, s[2:3]
	v_mov_b32_e32 v165, 0
	v_lshl_add_u64 v[132:133], v[0:1], 1, v[132:133]
	v_lshl_add_u64 v[134:135], v[132:133], 0, v[162:163]
	v_lshl_add_u64 v[136:137], v[132:133], 0, v[164:165]
	s_barrier
	global_load_dwordx4 v[132:135], v[134:135], off nt
	s_nop 0
	global_load_dwordx4 v[136:139], v[136:137], off nt
	v_mbcnt_lo_u32_b32 v3, -1, 0
	v_mbcnt_hi_u32_b32 v3, -1, v3
	v_and_b32_e32 v145, 64, v3
	v_xor_b32_e32 v144, 16, v3
	v_add_u32_e32 v170, 64, v145
	v_cmp_lt_i32_e32 vcc, v144, v170
	v_mov_b32_e32 v140, v165
	v_mov_b32_e32 v141, v165
	v_cndmask_b32_e32 v144, v3, v144, vcc
	v_lshlrev_b32_e32 v169, 2, v144
	v_mov_b32_e32 v142, v165
	v_mov_b32_e32 v143, v165
	s_lshl_b32 s4, s9, 2
	s_add_i32 s6, s4, 0x100
	s_waitcnt vmcnt(0)
	v_cndmask_b32_e64 v144, v136, v132, s[2:3]
	v_cndmask_b32_e64 v145, v137, v133, s[2:3]
	v_cndmask_b32_e64 v146, v138, v134, s[2:3]
	v_cndmask_b32_e64 v147, v139, v135, s[2:3]
	v_cndmask_b32_e64 v132, v132, v136, s[2:3]
	v_cndmask_b32_e64 v133, v133, v137, s[2:3]
	v_cndmask_b32_e64 v134, v134, v138, s[2:3]
	v_cndmask_b32_e64 v135, v135, v139, s[2:3]
	v_mov_b32_dpp v140, v132 row_ror:8 row_mask:0xf bank_mask:0xf
	v_mov_b32_dpp v141, v133 row_ror:8 row_mask:0xf bank_mask:0xf
	v_lshlrev_b32_e32 v136, 16, v146
	v_and_b32_e32 v137, 0xffff0000, v146
	v_lshlrev_b32_e32 v138, 16, v147
	v_and_b32_e32 v139, 0xffff0000, v147
	v_mov_b32_dpp v142, v134 row_ror:8 row_mask:0xf bank_mask:0xf
	v_mov_b32_dpp v143, v135 row_ror:8 row_mask:0xf bank_mask:0xf
	v_lshlrev_b32_e32 v132, 16, v144
	v_and_b32_e32 v133, 0xffff0000, v144
	v_lshlrev_b32_e32 v134, 16, v145
	v_and_b32_e32 v135, 0xffff0000, v145
	v_pk_add_f32 v[152:153], v[126:127], v[138:139]
	v_pk_add_f32 v[154:155], v[124:125], v[136:137]
	v_lshlrev_b32_e32 v124, 16, v140
	v_and_b32_e32 v125, 0xffff0000, v140
	v_lshlrev_b32_e32 v126, 16, v141
	v_and_b32_e32 v127, 0xffff0000, v141
	v_pk_add_f32 v[158:159], v[130:131], v[134:135]
	v_pk_add_f32 v[160:161], v[128:129], v[132:133]
	v_lshlrev_b32_e32 v128, 16, v142
	v_and_b32_e32 v129, 0xffff0000, v142
	v_pk_add_f32 v[148:149], v[122:123], v[126:127]
	v_pk_add_f32 v[150:151], v[120:121], v[124:125]
	v_lshlrev_b32_e32 v130, 16, v143
	v_and_b32_e32 v131, 0xffff0000, v143
	v_mul_f32_e32 v132, v161, v161
	v_mul_f32_e32 v133, v159, v159
	v_pk_add_f32 v[146:147], v[116:117], v[128:129]
	v_mul_f32_e32 v116, v151, v151
	v_mul_f32_e32 v117, v149, v149
	v_mul_f32_e32 v134, v155, v155
	v_pk_add_f32 v[144:145], v[118:119], v[130:131]
	v_fmac_f32_e32 v132, v160, v160
	v_fmac_f32_e32 v133, v158, v158
	v_mul_f32_e32 v118, v147, v147
	v_fmac_f32_e32 v116, v150, v150
	v_fmac_f32_e32 v117, v148, v148
	v_mul_f32_e32 v135, v153, v153
	v_fmac_f32_e32 v134, v154, v154
	v_mul_f32_e32 v119, v145, v145
	v_add_f32_e32 v120, v132, v133
	v_fmac_f32_e32 v118, v146, v146
	v_add_f32_e32 v116, v116, v117
	v_fmac_f32_e32 v135, v152, v152
	v_add_f32_e32 v120, v134, v120
	v_add_f32_e32 v116, v116, v118
	v_fmac_f32_e32 v119, v144, v144
	v_add_f32_e32 v117, v135, v120
	v_add_f32_e32 v116, v119, v116
	v_add_f32_e32 v116, v116, v117
	v_mov_b32_e32 v117, v116
	s_nop 1
	v_permlane16_swap_b32 v116, v117
	v_xor_b32_e32 v118, 32, v3
	v_cmp_lt_i32_e32 vcc, v118, v170
	v_lshl_add_u32 v170, v168, 4, s6
	s_nop 0
	v_cndmask_b32_e32 v3, v3, v118, vcc
	v_lshlrev_b32_e32 v171, 2, v3
	s_waitcnt lgkmcnt(0)
	v_add_f32_e32 v3, v116, v117
	v_mov_b32_e32 v116, v3
	s_nop 1
	v_permlane32_swap_b32 v3, v116
	v_cmp_gt_u32_e32 vcc, 16, v157
	s_and_saveexec_b64 s[4:5], vcc
	v_readlane_b32 s22, v254, 13
	v_readlane_b32 s23, v254, 14
	s_cbranch_execz .LBB0_1378
	s_waitcnt lgkmcnt(0)
	v_add_f32_e32 v3, v3, v116
	ds_write_b32 v170, v3
.LBB0_1378:
	s_or_b64 exec, exec, s[4:5]
	s_waitcnt lgkmcnt(0)
	v_or_b32_e32 v116, 16, v166
	v_ashrrev_i32_e32 v117, 31, v116
	v_lshlrev_b64 v[116:117], 11, v[116:117]
	v_lshl_add_u64 v[116:117], s[42:43], 0, v[116:117]
	v_lshl_add_u64 v[116:117], v[0:1], 1, v[116:117]
	v_lshl_add_u64 v[118:119], v[116:117], 0, v[162:163]
	v_lshl_add_u64 v[120:121], v[116:117], 0, v[164:165]
	global_load_dwordx4 v[116:119], v[118:119], off nt
	s_nop 0
	global_load_dwordx4 v[120:123], v[120:121], off nt
	v_mov_b32_e32 v3, v165
	v_mov_b32_e32 v124, v165
	v_mov_b32_e32 v125, v165
	v_mov_b32_e32 v126, v165
	s_waitcnt vmcnt(0)
	v_cndmask_b32_e64 v127, v120, v116, s[2:3]
	v_cndmask_b32_e64 v128, v121, v117, s[2:3]
	v_cndmask_b32_e64 v129, v122, v118, s[2:3]
	v_cndmask_b32_e64 v130, v123, v119, s[2:3]
	v_cndmask_b32_e64 v116, v116, v120, s[2:3]
	v_cndmask_b32_e64 v117, v117, v121, s[2:3]
	v_cndmask_b32_e64 v118, v118, v122, s[2:3]
	v_cndmask_b32_e64 v119, v119, v123, s[2:3]
	v_mov_b32_dpp v3, v116 row_ror:8 row_mask:0xf bank_mask:0xf
	v_mov_b32_dpp v124, v117 row_ror:8 row_mask:0xf bank_mask:0xf
	v_lshlrev_b32_e32 v120, 16, v129
	v_and_b32_e32 v121, 0xffff0000, v129
	v_lshlrev_b32_e32 v122, 16, v130
	v_and_b32_e32 v123, 0xffff0000, v130
	v_mov_b32_dpp v125, v118 row_ror:8 row_mask:0xf bank_mask:0xf
	v_mov_b32_dpp v126, v119 row_ror:8 row_mask:0xf bank_mask:0xf
	v_lshlrev_b32_e32 v116, 16, v127
	v_and_b32_e32 v117, 0xffff0000, v127
	v_lshlrev_b32_e32 v118, 16, v128
	v_and_b32_e32 v119, 0xffff0000, v128
	v_pk_add_f32 v[136:137], v[110:111], v[122:123]
	v_pk_add_f32 v[138:139], v[108:109], v[120:121]
	v_lshlrev_b32_e32 v108, 16, v3
	v_and_b32_e32 v109, 0xffff0000, v3
	v_lshlrev_b32_e32 v110, 16, v124
	v_and_b32_e32 v111, 0xffff0000, v124
	v_pk_add_f32 v[140:141], v[114:115], v[118:119]
	v_pk_add_f32 v[142:143], v[112:113], v[116:117]
	v_lshlrev_b32_e32 v112, 16, v125
	v_and_b32_e32 v113, 0xffff0000, v125
	v_pk_add_f32 v[132:133], v[106:107], v[110:111]
	v_pk_add_f32 v[134:135], v[104:105], v[108:109]
	v_lshlrev_b32_e32 v114, 16, v126
	v_and_b32_e32 v115, 0xffff0000, v126
	v_mul_f32_e32 v3, v143, v143
	v_mul_f32_e32 v116, v141, v141
	v_pk_add_f32 v[130:131], v[100:101], v[112:113]
	v_mul_f32_e32 v100, v135, v135
	v_mul_f32_e32 v101, v133, v133
	v_mul_f32_e32 v117, v139, v139
	v_pk_add_f32 v[126:127], v[102:103], v[114:115]
	v_fmac_f32_e32 v3, v142, v142
	v_fmac_f32_e32 v116, v140, v140
	v_mul_f32_e32 v102, v131, v131
	v_fmac_f32_e32 v100, v134, v134
	v_fmac_f32_e32 v101, v132, v132
	v_mul_f32_e32 v118, v137, v137
	v_fmac_f32_e32 v117, v138, v138
	v_mul_f32_e32 v103, v127, v127
	v_add_f32_e32 v3, v3, v116
	v_fmac_f32_e32 v102, v130, v130
	v_add_f32_e32 v100, v100, v101
	v_fmac_f32_e32 v118, v136, v136
	v_add_f32_e32 v3, v117, v3
	v_add_f32_e32 v100, v100, v102
	v_fmac_f32_e32 v103, v126, v126
	v_add_f32_e32 v3, v118, v3
	v_add_f32_e32 v100, v103, v100
	v_add_f32_e32 v3, v100, v3
	v_mov_b32_e32 v100, v3
	s_nop 1
	v_permlane16_swap_b32 v3, v100
	s_waitcnt lgkmcnt(0)
	v_add_f32_e32 v3, v3, v100
	v_mov_b32_e32 v100, v3
	s_nop 1
	v_permlane32_swap_b32 v3, v100
	s_and_saveexec_b64 s[4:5], vcc
	s_cbranch_execz .LBB0_1380
	s_waitcnt lgkmcnt(0)
	v_add_f32_e32 v3, v3, v100
	ds_write_b32 v170, v3 offset:256
.LBB0_1380:
	s_or_b64 exec, exec, s[4:5]
	s_waitcnt lgkmcnt(0)
	v_or_b32_e32 v100, 32, v166
	v_ashrrev_i32_e32 v101, 31, v100
	v_lshlrev_b64 v[100:101], 11, v[100:101]
	v_lshl_add_u64 v[100:101], s[42:43], 0, v[100:101]
	v_lshl_add_u64 v[100:101], v[0:1], 1, v[100:101]
	v_lshl_add_u64 v[102:103], v[100:101], 0, v[162:163]
	v_lshl_add_u64 v[104:105], v[100:101], 0, v[164:165]
	global_load_dwordx4 v[100:103], v[102:103], off nt
	s_nop 0
	global_load_dwordx4 v[104:107], v[104:105], off nt
	v_mov_b32_e32 v3, 0
	v_mov_b32_e32 v108, 0
	v_mov_b32_e32 v109, 0
	v_mov_b32_e32 v110, 0
	s_waitcnt vmcnt(0)
	v_cndmask_b32_e64 v111, v104, v100, s[2:3]
	v_cndmask_b32_e64 v112, v105, v101, s[2:3]
	v_cndmask_b32_e64 v113, v106, v102, s[2:3]
	v_cndmask_b32_e64 v114, v107, v103, s[2:3]
	v_cndmask_b32_e64 v100, v100, v104, s[2:3]
	v_cndmask_b32_e64 v101, v101, v105, s[2:3]
	v_cndmask_b32_e64 v102, v102, v106, s[2:3]
	v_cndmask_b32_e64 v103, v103, v107, s[2:3]
	v_mov_b32_dpp v3, v100 row_ror:8 row_mask:0xf bank_mask:0xf
	v_mov_b32_dpp v108, v101 row_ror:8 row_mask:0xf bank_mask:0xf
	v_lshlrev_b32_e32 v104, 16, v113
	v_and_b32_e32 v105, 0xffff0000, v113
	v_lshlrev_b32_e32 v106, 16, v114
	v_and_b32_e32 v107, 0xffff0000, v114
	v_mov_b32_dpp v109, v102 row_ror:8 row_mask:0xf bank_mask:0xf
	v_mov_b32_dpp v110, v103 row_ror:8 row_mask:0xf bank_mask:0xf
	v_lshlrev_b32_e32 v100, 16, v111
	v_and_b32_e32 v101, 0xffff0000, v111
	v_lshlrev_b32_e32 v102, 16, v112
	v_and_b32_e32 v103, 0xffff0000, v112
	v_pk_add_f32 v[120:121], v[94:95], v[106:107]
	v_pk_add_f32 v[122:123], v[92:93], v[104:105]
	v_lshlrev_b32_e32 v92, 16, v3
	v_and_b32_e32 v93, 0xffff0000, v3
	v_lshlrev_b32_e32 v94, 16, v108
	v_and_b32_e32 v95, 0xffff0000, v108
	v_pk_add_f32 v[124:125], v[98:99], v[102:103]
	v_pk_add_f32 v[128:129], v[96:97], v[100:101]
	v_lshlrev_b32_e32 v96, 16, v109
	v_and_b32_e32 v97, 0xffff0000, v109
	v_pk_add_f32 v[116:117], v[90:91], v[94:95]
	v_pk_add_f32 v[118:119], v[88:89], v[92:93]
	v_lshlrev_b32_e32 v98, 16, v110
	v_and_b32_e32 v99, 0xffff0000, v110
	v_mul_f32_e32 v3, v129, v129
	v_mul_f32_e32 v100, v125, v125
	v_pk_add_f32 v[114:115], v[84:85], v[96:97]
	v_mul_f32_e32 v84, v119, v119
	v_mul_f32_e32 v85, v117, v117
	v_mul_f32_e32 v101, v123, v123
	v_pk_add_f32 v[112:113], v[86:87], v[98:99]
	v_fmac_f32_e32 v3, v128, v128
	v_fmac_f32_e32 v100, v124, v124
	v_mul_f32_e32 v86, v115, v115
	v_fmac_f32_e32 v84, v118, v118
	v_fmac_f32_e32 v85, v116, v116
	v_mul_f32_e32 v102, v121, v121
	v_fmac_f32_e32 v101, v122, v122
	v_mul_f32_e32 v87, v113, v113
	v_add_f32_e32 v3, v3, v100
	v_fmac_f32_e32 v86, v114, v114
	v_add_f32_e32 v84, v84, v85
	v_fmac_f32_e32 v102, v120, v120
	v_add_f32_e32 v3, v101, v3
	v_add_f32_e32 v84, v84, v86
	v_fmac_f32_e32 v87, v112, v112
	v_add_f32_e32 v3, v102, v3
	v_add_f32_e32 v84, v87, v84
	v_add_f32_e32 v3, v84, v3
	v_mov_b32_e32 v84, v3
	s_nop 1
	v_permlane16_swap_b32 v3, v84
	s_waitcnt lgkmcnt(0)
	v_add_f32_e32 v84, v3, v84
	v_mov_b32_e32 v85, v84
	s_nop 1
	v_permlane32_swap_b32 v84, v85
	v_mov_b32_e32 v3, 0
	s_and_saveexec_b64 s[4:5], vcc
	s_cbranch_execz .LBB0_1382
	s_waitcnt lgkmcnt(0)
	v_add_f32_e32 v84, v84, v85
	ds_write_b32 v170, v84 offset:512
.LBB0_1382:
	s_or_b64 exec, exec, s[4:5]
	v_or_b32_e32 v84, 48, v166
	s_waitcnt lgkmcnt(0)
	v_ashrrev_i32_e32 v85, 31, v84
	v_lshlrev_b64 v[84:85], 11, v[84:85]
	v_lshl_add_u64 v[84:85], s[42:43], 0, v[84:85]
	v_lshl_add_u64 v[84:85], v[0:1], 1, v[84:85]
	v_lshl_add_u64 v[86:87], v[84:85], 0, v[162:163]
	v_lshl_add_u64 v[88:89], v[84:85], 0, v[164:165]
	global_load_dwordx4 v[84:87], v[86:87], off nt
	s_nop 0
	global_load_dwordx4 v[88:91], v[88:89], off nt
	v_mov_b32_e32 v92, 0
	v_mov_b32_e32 v93, 0
	v_mov_b32_e32 v94, 0
	s_waitcnt vmcnt(0)
	v_cndmask_b32_e64 v95, v88, v84, s[2:3]
	v_cndmask_b32_e64 v96, v89, v85, s[2:3]
	v_cndmask_b32_e64 v97, v90, v86, s[2:3]
	v_cndmask_b32_e64 v98, v91, v87, s[2:3]
	v_cndmask_b32_e64 v84, v84, v88, s[2:3]
	v_cndmask_b32_e64 v85, v85, v89, s[2:3]
	v_cndmask_b32_e64 v86, v86, v90, s[2:3]
	v_cndmask_b32_e64 v87, v87, v91, s[2:3]
	v_mov_b32_dpp v92, v84 row_ror:8 row_mask:0xf bank_mask:0xf
	v_mov_b32_dpp v93, v85 row_ror:8 row_mask:0xf bank_mask:0xf
	v_lshlrev_b32_e32 v88, 16, v97
	v_and_b32_e32 v89, 0xffff0000, v97
	v_lshlrev_b32_e32 v90, 16, v98
	v_and_b32_e32 v91, 0xffff0000, v98
	v_mov_b32_dpp v94, v86 row_ror:8 row_mask:0xf bank_mask:0xf
	v_mov_b32_dpp v3, v87 row_ror:8 row_mask:0xf bank_mask:0xf
	v_lshlrev_b32_e32 v84, 16, v95
	v_and_b32_e32 v85, 0xffff0000, v95
	v_lshlrev_b32_e32 v86, 16, v96
	v_and_b32_e32 v87, 0xffff0000, v96
	v_pk_add_f32 v[104:105], v[78:79], v[90:91]
	v_pk_add_f32 v[106:107], v[76:77], v[88:89]
	v_lshlrev_b32_e32 v76, 16, v92
	v_and_b32_e32 v77, 0xffff0000, v92
	v_lshlrev_b32_e32 v78, 16, v93
	v_and_b32_e32 v79, 0xffff0000, v93
	v_pk_add_f32 v[108:109], v[82:83], v[86:87]
	v_pk_add_f32 v[110:111], v[80:81], v[84:85]
	v_lshlrev_b32_e32 v80, 16, v94
	v_and_b32_e32 v81, 0xffff0000, v94
	v_pk_add_f32 v[100:101], v[74:75], v[78:79]
	v_pk_add_f32 v[102:103], v[72:73], v[76:77]
	v_lshlrev_b32_e32 v82, 16, v3
	v_and_b32_e32 v83, 0xffff0000, v3
	v_mul_f32_e32 v3, v111, v111
	v_mul_f32_e32 v84, v109, v109
	v_pk_add_f32 v[98:99], v[68:69], v[80:81]
	v_mul_f32_e32 v68, v103, v103
	v_mul_f32_e32 v69, v101, v101
	v_mul_f32_e32 v85, v107, v107
	v_pk_add_f32 v[94:95], v[70:71], v[82:83]
	v_fmac_f32_e32 v3, v110, v110
	v_fmac_f32_e32 v84, v108, v108
	v_mul_f32_e32 v70, v99, v99
	v_fmac_f32_e32 v68, v102, v102
	v_fmac_f32_e32 v69, v100, v100
	v_mul_f32_e32 v86, v105, v105
	v_fmac_f32_e32 v85, v106, v106
	v_mul_f32_e32 v71, v95, v95
	v_add_f32_e32 v3, v3, v84
	v_fmac_f32_e32 v70, v98, v98
	v_add_f32_e32 v68, v68, v69
	v_fmac_f32_e32 v86, v104, v104
	v_add_f32_e32 v3, v85, v3
	v_add_f32_e32 v68, v68, v70
	v_fmac_f32_e32 v71, v94, v94
	v_add_f32_e32 v3, v86, v3
	v_add_f32_e32 v68, v71, v68
	v_add_f32_e32 v3, v68, v3
	v_mov_b32_e32 v68, v3
	s_nop 1
	v_permlane16_swap_b32 v3, v68
	s_waitcnt lgkmcnt(0)
	v_add_f32_e32 v3, v3, v68
	v_mov_b32_e32 v68, v3
	s_nop 1
	v_permlane32_swap_b32 v3, v68
	s_and_saveexec_b64 s[4:5], vcc
	s_cbranch_execz .LBB0_1384
	s_waitcnt lgkmcnt(0)
	v_add_f32_e32 v3, v3, v68
	ds_write_b32 v170, v3 offset:768
.LBB0_1384:
	s_or_b64 exec, exec, s[4:5]
	s_waitcnt lgkmcnt(0)
	v_lshlrev_b64 v[68:69], 11, v[166:167]
	v_lshl_add_u64 v[68:69], s[42:43], 0, v[68:69]
	v_lshl_add_u64 v[68:69], v[0:1], 1, v[68:69]
	s_mov_b64 s[4:5], 0x40000
	v_lshl_add_u64 v[70:71], v[68:69], 0, s[4:5]
	v_lshl_add_u64 v[72:73], v[70:71], 0, v[162:163]
	v_lshl_add_u64 v[74:75], v[70:71], 0, v[164:165]
	global_load_dwordx4 v[70:73], v[72:73], off nt
	s_nop 0
	global_load_dwordx4 v[74:77], v[74:75], off nt
	v_mov_b32_e32 v3, 0
	v_mov_b32_e32 v78, 0
	v_mov_b32_e32 v79, 0
	v_mov_b32_e32 v80, 0
	s_waitcnt vmcnt(0)
	v_cndmask_b32_e64 v81, v74, v70, s[2:3]
	v_cndmask_b32_e64 v82, v75, v71, s[2:3]
	v_cndmask_b32_e64 v83, v76, v72, s[2:3]
	v_cndmask_b32_e64 v84, v77, v73, s[2:3]
	v_cndmask_b32_e64 v70, v70, v74, s[2:3]
	v_cndmask_b32_e64 v71, v71, v75, s[2:3]
	v_cndmask_b32_e64 v72, v72, v76, s[2:3]
	v_cndmask_b32_e64 v73, v73, v77, s[2:3]
	v_mov_b32_dpp v3, v70 row_ror:8 row_mask:0xf bank_mask:0xf
	v_mov_b32_dpp v78, v71 row_ror:8 row_mask:0xf bank_mask:0xf
	v_lshlrev_b32_e32 v74, 16, v83
	v_and_b32_e32 v75, 0xffff0000, v83
	v_lshlrev_b32_e32 v76, 16, v84
	v_and_b32_e32 v77, 0xffff0000, v84
	v_mov_b32_dpp v79, v72 row_ror:8 row_mask:0xf bank_mask:0xf
	v_mov_b32_dpp v80, v73 row_ror:8 row_mask:0xf bank_mask:0xf
	v_lshlrev_b32_e32 v70, 16, v81
	v_and_b32_e32 v71, 0xffff0000, v81
	v_lshlrev_b32_e32 v72, 16, v82
	v_and_b32_e32 v73, 0xffff0000, v82
	v_pk_add_f32 v[88:89], v[62:63], v[76:77]
	v_pk_add_f32 v[90:91], v[60:61], v[74:75]
	v_lshlrev_b32_e32 v60, 16, v3
	v_and_b32_e32 v61, 0xffff0000, v3
	v_lshlrev_b32_e32 v62, 16, v78
	v_and_b32_e32 v63, 0xffff0000, v78
	v_pk_add_f32 v[92:93], v[66:67], v[72:73]
	v_pk_add_f32 v[96:97], v[64:65], v[70:71]
	v_lshlrev_b32_e32 v64, 16, v79
	v_and_b32_e32 v65, 0xffff0000, v79
	v_pk_add_f32 v[84:85], v[58:59], v[62:63]
	v_pk_add_f32 v[86:87], v[56:57], v[60:61]
	v_lshlrev_b32_e32 v66, 16, v80
	v_and_b32_e32 v67, 0xffff0000, v80
	v_mul_f32_e32 v3, v97, v97
	v_mul_f32_e32 v70, v93, v93
	v_pk_add_f32 v[82:83], v[52:53], v[64:65]
	v_mul_f32_e32 v52, v87, v87
	v_mul_f32_e32 v53, v85, v85
	v_mul_f32_e32 v71, v91, v91
	v_pk_add_f32 v[80:81], v[54:55], v[66:67]
	v_fmac_f32_e32 v3, v96, v96
	v_fmac_f32_e32 v70, v92, v92
	v_mul_f32_e32 v54, v83, v83
	v_fmac_f32_e32 v52, v86, v86
	v_fmac_f32_e32 v53, v84, v84
	v_mul_f32_e32 v72, v89, v89
	v_fmac_f32_e32 v71, v90, v90
	v_mul_f32_e32 v55, v81, v81
	v_add_f32_e32 v3, v3, v70
	v_fmac_f32_e32 v54, v82, v82
	v_add_f32_e32 v52, v52, v53
	v_fmac_f32_e32 v72, v88, v88
	v_add_f32_e32 v3, v71, v3
	v_add_f32_e32 v52, v52, v54
	v_fmac_f32_e32 v55, v80, v80
	v_add_f32_e32 v3, v72, v3
	v_add_f32_e32 v52, v55, v52
	v_add_f32_e32 v3, v52, v3
	v_mov_b32_e32 v52, v3
	s_nop 1
	v_permlane16_swap_b32 v3, v52
	s_waitcnt lgkmcnt(0)
	v_add_f32_e32 v53, v3, v52
	v_mov_b32_e32 v54, v53
	s_nop 1
	v_permlane32_swap_b32 v53, v54
	v_add_u32_e32 v3, 0x80, v168
	v_mov_b32_e32 v52, 0
	s_and_saveexec_b64 s[4:5], vcc
	s_cbranch_execz .LBB0_1386
	v_lshl_add_u32 v55, v3, 4, s6
	s_waitcnt lgkmcnt(0)
	v_add_f32_e32 v53, v53, v54
	ds_write_b32 v55, v53
.LBB0_1386:
	s_or_b64 exec, exec, s[4:5]
	s_mov_b64 s[4:5], 0x48000
	s_waitcnt lgkmcnt(0)
	v_lshl_add_u64 v[54:55], v[68:69], 0, s[4:5]
	v_lshl_add_u64 v[56:57], v[54:55], 0, v[162:163]
	v_lshl_add_u64 v[58:59], v[54:55], 0, v[164:165]
	global_load_dwordx4 v[54:57], v[56:57], off nt
	s_nop 0
	global_load_dwordx4 v[58:61], v[58:59], off nt
	v_mov_b32_e32 v53, 0
	v_mov_b32_e32 v62, 0
	v_mov_b32_e32 v63, 0
	s_waitcnt vmcnt(0)
	v_cndmask_b32_e64 v64, v58, v54, s[2:3]
	v_cndmask_b32_e64 v65, v59, v55, s[2:3]
	v_cndmask_b32_e64 v66, v60, v56, s[2:3]
	v_cndmask_b32_e64 v67, v61, v57, s[2:3]
	v_cndmask_b32_e64 v54, v54, v58, s[2:3]
	v_cndmask_b32_e64 v55, v55, v59, s[2:3]
	v_cndmask_b32_e64 v56, v56, v60, s[2:3]
	v_cndmask_b32_e64 v57, v57, v61, s[2:3]
	v_mov_b32_dpp v53, v54 row_ror:8 row_mask:0xf bank_mask:0xf
	v_mov_b32_dpp v62, v55 row_ror:8 row_mask:0xf bank_mask:0xf
	v_lshlrev_b32_e32 v58, 16, v66
	v_and_b32_e32 v59, 0xffff0000, v66
	v_lshlrev_b32_e32 v60, 16, v67
	v_and_b32_e32 v61, 0xffff0000, v67
	v_mov_b32_dpp v63, v56 row_ror:8 row_mask:0xf bank_mask:0xf
	v_mov_b32_dpp v52, v57 row_ror:8 row_mask:0xf bank_mask:0xf
	v_lshlrev_b32_e32 v54, 16, v64
	v_and_b32_e32 v55, 0xffff0000, v64
	v_lshlrev_b32_e32 v56, 16, v65
	v_and_b32_e32 v57, 0xffff0000, v65
	v_pk_add_f32 v[72:73], v[46:47], v[60:61]
	v_pk_add_f32 v[74:75], v[44:45], v[58:59]
	v_lshlrev_b32_e32 v44, 16, v53
	v_and_b32_e32 v45, 0xffff0000, v53
	v_lshlrev_b32_e32 v46, 16, v62
	v_and_b32_e32 v47, 0xffff0000, v62
	v_pk_add_f32 v[76:77], v[50:51], v[56:57]
	v_pk_add_f32 v[78:79], v[48:49], v[54:55]
	v_lshlrev_b32_e32 v48, 16, v63
	v_and_b32_e32 v49, 0xffff0000, v63
	v_pk_add_f32 v[68:69], v[42:43], v[46:47]
	v_pk_add_f32 v[70:71], v[40:41], v[44:45]
	v_lshlrev_b32_e32 v50, 16, v52
	v_and_b32_e32 v51, 0xffff0000, v52
	v_mul_f32_e32 v52, v79, v79
	v_mul_f32_e32 v53, v77, v77
	v_pk_add_f32 v[66:67], v[36:37], v[48:49]
	v_mul_f32_e32 v36, v71, v71
	v_mul_f32_e32 v37, v69, v69
	v_mul_f32_e32 v54, v75, v75
	v_pk_add_f32 v[62:63], v[38:39], v[50:51]
	v_fmac_f32_e32 v52, v78, v78
	v_fmac_f32_e32 v53, v76, v76
	v_mul_f32_e32 v38, v67, v67
	v_fmac_f32_e32 v36, v70, v70
	v_fmac_f32_e32 v37, v68, v68
	v_mul_f32_e32 v55, v73, v73
	v_fmac_f32_e32 v54, v74, v74
	v_mul_f32_e32 v39, v63, v63
	v_add_f32_e32 v40, v52, v53
	v_fmac_f32_e32 v38, v66, v66
	v_add_f32_e32 v36, v36, v37
	v_fmac_f32_e32 v55, v72, v72
	v_add_f32_e32 v40, v54, v40
	v_add_f32_e32 v36, v36, v38
	v_fmac_f32_e32 v39, v62, v62
	v_add_f32_e32 v37, v55, v40
	v_add_f32_e32 v36, v39, v36
	v_add_f32_e32 v36, v36, v37
	v_mov_b32_e32 v37, v36
	s_nop 1
	v_permlane16_swap_b32 v36, v37
	s_waitcnt lgkmcnt(0)
	v_add_f32_e32 v36, v36, v37
	v_mov_b32_e32 v37, v36
	s_nop 1
	v_permlane32_swap_b32 v36, v37
	s_and_saveexec_b64 s[4:5], vcc
	s_cbranch_execz .LBB0_1388
	s_waitcnt lgkmcnt(0)
	v_add_f32_e32 v36, v36, v37
	ds_write_b32 v170, v36 offset:2304
.LBB0_1388:
	s_or_b64 exec, exec, s[4:5]
	s_waitcnt lgkmcnt(0)
	v_lshlrev_b64 v[36:37], 11, v[166:167]
	v_lshl_add_u64 v[36:37], s[42:43], 0, v[36:37]
	v_lshl_add_u64 v[36:37], v[0:1], 1, v[36:37]
	s_mov_b64 s[4:5], 0x50000
	v_lshl_add_u64 v[38:39], v[36:37], 0, s[4:5]
	v_lshl_add_u64 v[40:41], v[38:39], 0, v[162:163]
	v_lshl_add_u64 v[42:43], v[38:39], 0, v[164:165]
	global_load_dwordx4 v[38:41], v[40:41], off nt
	s_nop 0
	global_load_dwordx4 v[42:45], v[42:43], off nt
	v_mov_b32_e32 v46, 0
	v_mov_b32_e32 v47, 0
	v_mov_b32_e32 v48, 0
	v_mov_b32_e32 v49, 0
	s_waitcnt vmcnt(0)
	v_cndmask_b32_e64 v50, v42, v38, s[2:3]
	v_cndmask_b32_e64 v51, v43, v39, s[2:3]
	v_cndmask_b32_e64 v52, v44, v40, s[2:3]
	v_cndmask_b32_e64 v53, v45, v41, s[2:3]
	v_cndmask_b32_e64 v38, v38, v42, s[2:3]
	v_cndmask_b32_e64 v39, v39, v43, s[2:3]
	v_cndmask_b32_e64 v40, v40, v44, s[2:3]
	v_cndmask_b32_e64 v41, v41, v45, s[2:3]
	v_mov_b32_dpp v46, v38 row_ror:8 row_mask:0xf bank_mask:0xf
	v_mov_b32_dpp v47, v39 row_ror:8 row_mask:0xf bank_mask:0xf
	v_lshlrev_b32_e32 v42, 16, v52
	v_and_b32_e32 v43, 0xffff0000, v52
	v_lshlrev_b32_e32 v44, 16, v53
	v_and_b32_e32 v45, 0xffff0000, v53
	v_mov_b32_dpp v48, v40 row_ror:8 row_mask:0xf bank_mask:0xf
	v_mov_b32_dpp v49, v41 row_ror:8 row_mask:0xf bank_mask:0xf
	v_lshlrev_b32_e32 v38, 16, v50
	v_and_b32_e32 v39, 0xffff0000, v50
	v_lshlrev_b32_e32 v40, 16, v51
	v_and_b32_e32 v41, 0xffff0000, v51
	v_pk_add_f32 v[56:57], v[30:31], v[44:45]
	v_pk_add_f32 v[58:59], v[28:29], v[42:43]
	v_lshlrev_b32_e32 v28, 16, v46
	v_and_b32_e32 v29, 0xffff0000, v46
	v_lshlrev_b32_e32 v30, 16, v47
	v_and_b32_e32 v31, 0xffff0000, v47
	v_pk_add_f32 v[60:61], v[34:35], v[40:41]
	v_pk_add_f32 v[64:65], v[32:33], v[38:39]
	v_lshlrev_b32_e32 v32, 16, v48
	v_and_b32_e32 v33, 0xffff0000, v48
	v_pk_add_f32 v[52:53], v[26:27], v[30:31]
	v_pk_add_f32 v[54:55], v[24:25], v[28:29]
	v_lshlrev_b32_e32 v34, 16, v49
	v_and_b32_e32 v35, 0xffff0000, v49
	v_mul_f32_e32 v38, v65, v65
	v_mul_f32_e32 v39, v61, v61
	v_pk_add_f32 v[50:51], v[20:21], v[32:33]
	v_mul_f32_e32 v20, v55, v55
	v_mul_f32_e32 v21, v53, v53
	v_mul_f32_e32 v40, v59, v59
	v_pk_add_f32 v[48:49], v[22:23], v[34:35]
	v_fmac_f32_e32 v38, v64, v64
	v_fmac_f32_e32 v39, v60, v60
	v_mul_f32_e32 v22, v51, v51
	v_fmac_f32_e32 v20, v54, v54
	v_fmac_f32_e32 v21, v52, v52
	v_mul_f32_e32 v41, v57, v57
	v_fmac_f32_e32 v40, v58, v58
	v_mul_f32_e32 v23, v49, v49
	v_add_f32_e32 v24, v38, v39
	v_fmac_f32_e32 v22, v50, v50
	v_add_f32_e32 v20, v20, v21
	v_fmac_f32_e32 v41, v56, v56
	v_add_f32_e32 v24, v40, v24
	v_add_f32_e32 v20, v20, v22
	v_fmac_f32_e32 v23, v48, v48
	v_add_f32_e32 v21, v41, v24
	v_add_f32_e32 v20, v23, v20
	v_add_f32_e32 v20, v20, v21
	v_mov_b32_e32 v21, v20
	s_nop 1
	v_permlane16_swap_b32 v20, v21
	s_waitcnt lgkmcnt(0)
	v_add_f32_e32 v21, v20, v21
	v_mov_b32_e32 v22, v21
	s_nop 1
	v_permlane32_swap_b32 v21, v22
	v_mov_b32_e32 v20, 0
	s_and_saveexec_b64 s[4:5], vcc
	s_cbranch_execz .LBB0_1390
	s_waitcnt lgkmcnt(0)
	v_add_f32_e32 v21, v21, v22
	ds_write_b32 v170, v21 offset:2560
.LBB0_1390:
	s_or_b64 exec, exec, s[4:5]
	s_mov_b64 s[4:5], 0x58000
	s_waitcnt lgkmcnt(0)
	v_lshl_add_u64 v[22:23], v[36:37], 0, s[4:5]
	v_lshl_add_u64 v[24:25], v[22:23], 0, v[162:163]
	v_lshl_add_u64 v[26:27], v[22:23], 0, v[164:165]
	global_load_dwordx4 v[22:25], v[24:25], off nt
	s_nop 0
	global_load_dwordx4 v[26:29], v[26:27], off nt
	v_mov_b32_e32 v21, 0
	v_mov_b32_e32 v30, 0
	v_mov_b32_e32 v31, 0
	s_waitcnt vmcnt(0)
	v_cndmask_b32_e64 v32, v26, v22, s[2:3]
	v_cndmask_b32_e64 v33, v27, v23, s[2:3]
	v_cndmask_b32_e64 v34, v28, v24, s[2:3]
	v_cndmask_b32_e64 v35, v29, v25, s[2:3]
	v_cndmask_b32_e64 v22, v22, v26, s[2:3]
	v_cndmask_b32_e64 v23, v23, v27, s[2:3]
	v_cndmask_b32_e64 v24, v24, v28, s[2:3]
	v_cndmask_b32_e64 v25, v25, v29, s[2:3]
	v_mov_b32_dpp v21, v22 row_ror:8 row_mask:0xf bank_mask:0xf
	v_mov_b32_dpp v30, v23 row_ror:8 row_mask:0xf bank_mask:0xf
	v_lshlrev_b32_e32 v26, 16, v34
	v_and_b32_e32 v27, 0xffff0000, v34
	v_lshlrev_b32_e32 v28, 16, v35
	v_and_b32_e32 v29, 0xffff0000, v35
	v_mov_b32_dpp v31, v24 row_ror:8 row_mask:0xf bank_mask:0xf
	v_mov_b32_dpp v20, v25 row_ror:8 row_mask:0xf bank_mask:0xf
	v_lshlrev_b32_e32 v22, 16, v32
	v_and_b32_e32 v23, 0xffff0000, v32
	v_lshlrev_b32_e32 v24, 16, v33
	v_and_b32_e32 v25, 0xffff0000, v33
	v_pk_add_f32 v[40:41], v[14:15], v[28:29]
	v_pk_add_f32 v[42:43], v[12:13], v[26:27]
	v_lshlrev_b32_e32 v12, 16, v21
	v_and_b32_e32 v13, 0xffff0000, v21
	v_lshlrev_b32_e32 v14, 16, v30
	v_and_b32_e32 v15, 0xffff0000, v30
	v_pk_add_f32 v[44:45], v[18:19], v[24:25]
	v_pk_add_f32 v[46:47], v[16:17], v[22:23]
	v_lshlrev_b32_e32 v16, 16, v31
	v_and_b32_e32 v17, 0xffff0000, v31
	v_pk_add_f32 v[36:37], v[10:11], v[14:15]
	v_pk_add_f32 v[38:39], v[8:9], v[12:13]
	v_lshlrev_b32_e32 v18, 16, v20
	v_and_b32_e32 v19, 0xffff0000, v20
	v_mul_f32_e32 v20, v47, v47
	v_mul_f32_e32 v21, v45, v45
	v_pk_add_f32 v[34:35], v[4:5], v[16:17]
	v_mul_f32_e32 v4, v39, v39
	v_mul_f32_e32 v5, v37, v37
	v_mul_f32_e32 v22, v43, v43
	v_pk_add_f32 v[32:33], v[6:7], v[18:19]
	v_fmac_f32_e32 v20, v46, v46
	v_fmac_f32_e32 v21, v44, v44
	v_mul_f32_e32 v6, v35, v35
	v_fmac_f32_e32 v4, v38, v38
	v_fmac_f32_e32 v5, v36, v36
	v_mul_f32_e32 v23, v41, v41
	v_fmac_f32_e32 v22, v42, v42
	v_mul_f32_e32 v7, v33, v33
	v_add_f32_e32 v8, v20, v21
	v_fmac_f32_e32 v6, v34, v34
	v_add_f32_e32 v4, v4, v5
	v_fmac_f32_e32 v23, v40, v40
	v_add_f32_e32 v8, v22, v8
	v_add_f32_e32 v4, v4, v6
	v_fmac_f32_e32 v7, v32, v32
	v_add_f32_e32 v5, v23, v8
	v_add_f32_e32 v4, v7, v4
	v_add_f32_e32 v4, v4, v5
	v_mov_b32_e32 v5, v4
	s_nop 1
	v_permlane16_swap_b32 v4, v5
	s_waitcnt lgkmcnt(0)
	v_add_f32_e32 v4, v4, v5
	v_mov_b32_e32 v5, v4
	s_nop 1
	v_permlane32_swap_b32 v4, v5
	s_and_saveexec_b64 s[4:5], vcc
	s_cbranch_execz .LBB0_1392
	s_waitcnt lgkmcnt(0)
	v_add_f32_e32 v4, v4, v5
	ds_write_b32 v170, v4 offset:2816
